# e31: attention A waves default priority (was 3), B waves static s_setprio 2 for their tile loop; GEMM static priority waves 0-3
# speedup vs baseline: 1.0071x; 1.0071x over previous
; #define DMA_K(j_, b_) do { const char* kb_ = (const char*)Kh + (size_t)(j_) * (64 * LD * 2); _Pragma("unroll") for (int i = 0; i < 4; ++i) \
;     __builtin_amdgcn_global_load_lds((const unsigned*)(kb_ + kgo[i]), (LAS unsigned*)(K_las + (b_) * 16384 + (4 * a + i) * 1024), 16, 0, 0); } while (0)
; #define DMA_V(j_, b_) do { const char* vb_ = (const char*)Vh + (size_t)(j_) * (64 * LD * 2); _Pragma("unroll") for (int hf = 0; hf < 2; ++hf) _Pragma("unroll") for (int i = 0; i < 4; ++i) \
;     __builtin_amdgcn_global_load_lds((const unsigned*)(vb_ + hf * 256 + vgo[i]), (LAS unsigned*)(V_las + (b_) * 32768 + hf * 16384 + (4 * a + i) * 1024), 16, 0, 0); } while (0)
; __device__ __forceinline__ void attn_unit2(const bf16* __restrict__ Qb, const bf16* __restrict__ Kh, const bf16* __restrict__ Vh, bf16* __restrict__ Ob,
;                                            int NT, int lim, int qrow0, const float* lut, char* lds, float* scr) {
;     ...
;     const int rp = a >> 1, ch = a & 1;
;     const char* P0 = lds + 98304 + (2 * rp) * 4096; const float* al0 = scr + (2 * rp) * 32; const float* ll0 = scr + 256 + (2 * rp) * 32;
;     f32x16 o[2][4] = {};
;     for (int j = 0; j <= NT; ++j) {
;       if (j + 1 < NT) DMA_K(j + 1, (j + 1) & 1);
;       if (j < NT) DMA_V(j, j & 1);
;       if (j >= 1) {
.LBB0_430:
	s_and_b64 s[14:15], s[44:45], exec
	s_waitcnt vmcnt(0)
	s_cselect_b32 s87, s79, s78
	v_lshrrev_b32_e32 v141, 5, v173
	s_lshl_b32 s89, s87, 18
	s_lshl_b32 s88, s87, 1
	v_and_b32_e32 v172, 31, v7
	v_lshlrev_b32_e32 v174, 4, v173
	s_mov_b64 s[38:39], -1
	s_and_b64 vcc, exec, s[36:37]
	v_lshlrev_b32_e32 v140, 4, v141
	s_waitcnt vmcnt(0) lgkmcnt(0)
	s_barrier
	s_cbranch_vccz .LBB0_445
	s_bfe_u32 s91, s6, 0x10006
	s_add_i32 s6, s85, 0
	v_lshrrev_b32_e32 v2, 1, v7
	v_lshlrev_b32_e32 v16, 3, v7
	s_add_i32 m0, s6, 0x4000
	s_lshl_b32 s8, s86, 4
	v_bfe_u32 v14, v7, 2, 2
	v_and_b32_e32 v15, 8, v2
	v_and_b32_e32 v16, 24, v16
	global_load_lds_dwordx4 v8, s[18:19]
	s_add_i32 m0, s6, 0x4400
	v_or3_b32 v2, s8, v14, v15
	v_and_or_b32 v17, v7, 32, v16
	global_load_lds_dwordx4 v10, s[18:19]
	s_add_i32 m0, s6, 0x4800
	v_lshlrev_b32_e32 v18, 12, v2
	v_lshlrev_b32_e32 v17, 1, v17
	s_add_i32 s15, s6, 0x8000
	global_load_lds_dwordx4 v9, s[18:19]
	s_add_i32 m0, s6, 0x4c00
	v_or_b32_e32 v2, v18, v17
	v_and_or_b32 v12, v12, s22, v16
	global_load_lds_dwordx4 v11, s[18:19]
	s_mov_b32 m0, s15
	v_lshl_or_b32 v136, v12, 1, v18
	v_or_b32_e32 v12, 0x4000, v18
	global_load_lds_dwordx4 v2, s[12:13]
	s_add_i32 m0, s6, 0x8400
	v_or_b32_e32 v134, v12, v17
	v_and_or_b32 v13, v13, s22, v16
	global_load_lds_dwordx4 v136, s[12:13]
	s_add_i32 m0, s6, 0x8800
	v_lshl_or_b32 v132, v13, 1, v12
	v_lshl_add_u64 v[8:9], s[12:13], 0, v[2:3]
	v_mov_b32_e32 v137, v3
	global_load_lds_dwordx4 v134, s[12:13]
	s_add_i32 m0, s6, 0x8c00
	s_mov_b64 s[28:29], 0x100
	v_lshl_add_u64 v[10:11], s[12:13], 0, v[136:137]
	global_load_lds_dwordx4 v132, s[12:13]
	s_add_i32 m0, s6, 0xc000
	v_lshl_add_u64 v[8:9], v[8:9], 0, s[28:29]
	global_load_lds_dwordx4 v[8:9], off
	v_lshl_add_u64 v[8:9], v[10:11], 0, s[28:29]
	s_add_i32 m0, s6, 0xc400
	s_and_b32 s90, s4, 2
	global_load_lds_dwordx4 v[8:9], off
	s_add_i32 m0, s6, 0xc800
	s_lshl_b32 s4, s90, 12
	global_load_lds_dwordx4 v134, s[20:21]
	s_add_i32 m0, s6, 0xcc00
	s_add_i32 s4, s4, 0
	global_load_lds_dwordx4 v132, s[20:21]
	s_add_i32 s14, s4, 0x18000
	s_lshl_b32 s4, s90, 7
	s_add_i32 s4, s4, 0
	s_add_i32 s5, s88, 2
	s_lshl_b32 s92, s90, 5
	s_add_i32 s4, s4, 0x22000
	v_add_u32_e32 v175, s14, v174
	s_lshl_b32 s14, s91, 14
	s_add_i32 s15, 0, 0x8000
	v_lshlrev_b32_e32 v16, 1, v173
	s_cmp_lg_u32 s15, -1
	v_lshlrev_b32_e32 v12, 3, v173
	v_and_b32_e32 v13, 0xc0, v174
	v_and_b32_e32 v16, 32, v16
	s_cselect_b32 s15, s15, 0
	v_and_b32_e32 v12, 0x118, v12
	v_add3_u32 v8, v13, s15, v16
	v_add3_u32 v176, v8, v12, s14
	v_or3_b32 v8, s8, v15, v14
	v_lshlrev_b32_e32 v10, 12, v8
	v_lshlrev_b32_e32 v8, 1, v7
	v_lshlrev_b32_e32 v7, 4, v7
	v_and_b32_e32 v11, 64, v8
	v_and_b32_e32 v7, 48, v7
	v_or3_b32 v8, v10, v11, v7
	v_mov_b32_e32 v9, v3
	v_add3_u32 v12, s9, 64, v173
	v_lshl_add_u64 v[138:139], s[40:41], 0, v[8:9]
	v_lshlrev_b32_e32 v8, 1, v12
	v_and_b32_e32 v8, 0xc0, v8
	v_or3_b32 v8, v10, v8, v7
	v_or_b32_e32 v10, 0x4000, v10
	s_add_i32 s8, s9, 0xc0
	v_lshl_add_u64 v[142:143], s[40:41], 0, v[8:9]
	v_or3_b32 v8, v10, v11, v7
	v_add_u32_e32 v11, s8, v173
	v_lshl_add_u64 v[144:145], s[40:41], 0, v[8:9]
	v_lshlrev_b32_e32 v8, 1, v11
	v_and_b32_e32 v8, 0xc0, v8
	v_or3_b32 v8, v10, v8, v7
	v_add_lshl_u32 v7, s9, v173, 8
	s_mov_b32 s9, 0x7f000
	v_and_or_b32 v6, v7, s9, v6
	v_mov_b32_e32 v7, v3
	v_lshl_add_u64 v[148:149], s[42:43], 0, v[6:7]
	v_lshlrev_b32_e32 v7, 8, v12
	s_mov_b32 s9, 0xff000
	v_lshl_add_u64 v[146:147], s[40:41], 0, v[8:9]
	v_and_or_b32 v8, v7, s9, v5
	v_lshlrev_b32_e32 v5, 8, v11
	s_waitcnt vmcnt(0)
	v_add_u32_e32 v6, 0x8000, v6
	v_mov_b32_e32 v7, v3
	v_and_or_b32 v4, v5, s9, v4
	v_mov_b32_e32 v5, v3
	v_mov_b32_e32 v18, v3
	v_mov_b32_e32 v19, v3
	s_lshl_b32 s8, s87, 19
	v_lshl_add_u64 v[150:151], s[42:43], 0, v[8:9]
	v_lshl_add_u64 v[152:153], s[42:43], 0, v[6:7]
	v_lshl_add_u64 v[154:155], s[42:43], 0, v[4:5]
	v_mov_b32_e32 v4, v3
	v_mov_b32_e32 v6, v3
	v_mov_b32_e32 v8, v3
	v_mov_b32_e32 v10, v3
	v_mov_b32_e32 v11, v3
	v_mov_b32_e32 v12, v3
	v_mov_b32_e32 v13, v3
	v_mov_b32_e32 v14, v3
	v_mov_b32_e32 v15, v3
	v_mov_b32_e32 v16, v3
	v_mov_b32_e32 v17, v3
	v_mov_b64_e32 v[34:35], v[18:19]
	v_mov_b64_e32 v[50:51], v[18:19]
	v_mov_b64_e32 v[66:67], v[18:19]
	v_mov_b64_e32 v[82:83], v[18:19]
	v_mov_b64_e32 v[98:99], v[18:19]
	v_mov_b64_e32 v[114:115], v[18:19]
	v_mov_b64_e32 v[130:131], v[18:19]
	s_mov_b32 s10, 2
	s_mov_b32 s7, 0x8000
	v_mov_b32_e32 v135, v3
	v_mov_b32_e32 v133, v3
	s_bitset1_b32 s8, 18
	s_mov_b64 s[36:37], 0
	s_mov_b32 s9, 0x8000
	v_mov_b64_e32 v[32:33], v[16:17]
	v_mov_b64_e32 v[30:31], v[14:15]
	v_mov_b64_e32 v[28:29], v[12:13]
	v_mov_b64_e32 v[26:27], v[10:11]
	v_mov_b64_e32 v[24:25], v[8:9]
	v_mov_b64_e32 v[22:23], v[6:7]
	v_mov_b64_e32 v[20:21], v[4:5]
	v_mov_b64_e32 v[48:49], v[16:17]
	v_mov_b64_e32 v[46:47], v[14:15]
	v_mov_b64_e32 v[44:45], v[12:13]
	v_mov_b64_e32 v[42:43], v[10:11]
	v_mov_b64_e32 v[40:41], v[8:9]
	v_mov_b64_e32 v[38:39], v[6:7]
	v_mov_b64_e32 v[36:37], v[4:5]
	v_mov_b64_e32 v[64:65], v[16:17]
	v_mov_b64_e32 v[62:63], v[14:15]
	v_mov_b64_e32 v[60:61], v[12:13]
	v_mov_b64_e32 v[58:59], v[10:11]
	v_mov_b64_e32 v[56:57], v[8:9]
	v_mov_b64_e32 v[54:55], v[6:7]
	v_mov_b64_e32 v[52:53], v[4:5]
	v_mov_b64_e32 v[80:81], v[16:17]
	v_mov_b64_e32 v[78:79], v[14:15]
	v_mov_b64_e32 v[76:77], v[12:13]
	v_mov_b64_e32 v[74:75], v[10:11]
	v_mov_b64_e32 v[72:73], v[8:9]
	v_mov_b64_e32 v[70:71], v[6:7]
	v_mov_b64_e32 v[68:69], v[4:5]
	v_mov_b64_e32 v[96:97], v[16:17]
	v_mov_b64_e32 v[94:95], v[14:15]
	v_mov_b64_e32 v[92:93], v[12:13]
	v_mov_b64_e32 v[90:91], v[10:11]
	v_mov_b64_e32 v[88:89], v[8:9]
	v_mov_b64_e32 v[86:87], v[6:7]
	v_mov_b64_e32 v[84:85], v[4:5]
	v_mov_b64_e32 v[112:113], v[16:17]
	v_mov_b64_e32 v[110:111], v[14:15]
	v_mov_b64_e32 v[108:109], v[12:13]
	v_mov_b64_e32 v[106:107], v[10:11]
	v_mov_b64_e32 v[104:105], v[8:9]
	v_mov_b64_e32 v[102:103], v[6:7]
	v_mov_b64_e32 v[100:101], v[4:5]
	v_mov_b64_e32 v[128:129], v[16:17]
	v_mov_b64_e32 v[126:127], v[14:15]
	v_mov_b64_e32 v[124:125], v[12:13]
	v_mov_b64_e32 v[122:123], v[10:11]
	v_mov_b64_e32 v[120:121], v[8:9]
	v_mov_b64_e32 v[118:119], v[6:7]
	v_mov_b64_e32 v[116:117], v[4:5]
	s_waitcnt vmcnt(0) lgkmcnt(0)
	s_barrier
	s_setprio 2
	s_nop 0
	s_nop 0
	s_nop 0
	s_nop 0
	s_nop 0
	s_nop 0
	s_nop 0
	s_nop 0
	s_nop 0
	s_nop 0
	s_nop 0
	s_nop 0
	s_nop 0
	s_nop 0
	s_nop 0
	s_cmp_lt_u32 s10, s5
	s_cselect_b64 s[38:39], -1, 0
	s_cmp_ge_u32 s10, s5
	s_cbranch_scc1 .LBB0_433

; #define DMA_K(j_, b_) do { const char* kb_ = (const char*)Kh + (size_t)(j_) * (64 * LD * 2); _Pragma("unroll") for (int i = 0; i < 4; ++i) \
;     __builtin_amdgcn_global_load_lds((const unsigned*)(kb_ + kgo[i]), (LAS unsigned*)(K_las + (b_) * 16384 + (4 * a + i) * 1024), 16, 0, 0); } while (0)
; #define DMA_V(j_, b_) do { const char* vb_ = (const char*)Vh + (size_t)(j_) * (64 * LD * 2); _Pragma("unroll") for (int hf = 0; hf < 2; ++hf) _Pragma("unroll") for (int i = 0; i < 4; ++i) \
;     __builtin_amdgcn_global_load_lds((const unsigned*)(vb_ + hf * 256 + vgo[i]), (LAS unsigned*)(V_las + (b_) * 32768 + hf * 16384 + (4 * a + i) * 1024), 16, 0, 0); } while (0)
; __device__ __forceinline__ void attn_unit2(const bf16* __restrict__ Qb, const bf16* __restrict__ Kh, const bf16* __restrict__ Vh, bf16* __restrict__ Ob,
;                                            int NT, int lim, int qrow0, const float* lut, char* lds, float* scr) {
;     ...
;       if (j + 1 < NT) DMA_K(j + 1, (j + 1) & 1);
;       if (j < NT) DMA_V(j, j & 1);
.LBB0_439:
	s_setprio 0
	s_andn2_b64 vcc, exec, s[38:39]
	s_cbranch_vccnz .LBB0_441
	s_lshl_b64 s[8:9], s[10:11], 18
	s_add_u32 s8, s12, s8
	s_addc_u32 s9, s13, s9
	s_lshl_b32 s5, s10, 15
	s_and_b32 s5, s5, 0x8000
	s_add_i32 s5, s6, s5
	s_add_i32 m0, s5, 0x8000
	v_lshl_add_u64 v[138:139], s[8:9], 0, v[2:3]
	global_load_lds_dwordx4 v[138:139], off
	v_lshl_add_u64 v[136:137], s[8:9], 0, v[136:137]
	s_add_i32 m0, s5, 0x8400
	v_lshl_add_u64 v[142:143], s[8:9], 0, v[134:135]
	global_load_lds_dwordx4 v[136:137], off
	s_add_i32 m0, s5, 0x8800
	s_nop 0
	global_load_lds_dwordx4 v[142:143], off
	s_add_i32 m0, s5, 0x8c00
	s_add_u32 s6, s8, 0x100
	v_lshl_add_u64 v[142:143], s[8:9], 0, v[132:133]
	s_addc_u32 s7, s9, 0
	s_mov_b64 s[8:9], 0x100
	global_load_lds_dwordx4 v[142:143], off
	s_add_i32 m0, s5, 0xc000
	v_lshl_add_u64 v[138:139], v[138:139], 0, s[8:9]
	global_load_lds_dwordx4 v[138:139], off
	v_lshl_add_u64 v[136:137], v[136:137], 0, s[8:9]
	s_add_i32 m0, s5, 0xc400
	v_lshl_add_u64 v[134:135], s[6:7], 0, v[134:135]
	global_load_lds_dwordx4 v[136:137], off
	s_add_i32 m0, s5, 0xc800
	v_lshl_add_u64 v[132:133], s[6:7], 0, v[132:133]
	global_load_lds_dwordx4 v[134:135], off
	s_add_i32 m0, s5, 0xcc00
	s_nop 0
	global_load_lds_dwordx4 v[132:133], off

; __device__ __forceinline__ int crow(int r, int hi) { return (r & 3) + 8 * (r >> 2) + 4 * hi; }
; __device__ __forceinline__ int crow(int r, int hi) { return (r & 3) + 8 * (r >> 2) + 4 * hi; }
; __device__ __forceinline__ void qkt(f32x16& p0, f32x16& p1, const char* Ks, const bf16x8* qr, int r32, int hi) {
;   p0 = f32x16{}; p1 = f32x16{};
; #pragma unroll
;   for (int d0 = 0; d0 < 8; ++d0) { int cb = (d0 * 16 + hi * 8) * 2;
;     bf16x8 b0 = *reinterpret_cast<const bf16x8*>(Ks + KSWZ(r32, cb));
;     bf16x8 b1 = *reinterpret_cast<const bf16x8*>(Ks + KSWZ(32 + r32, cb));
;     p0 = __builtin_amdgcn_mfma_f32_32x32x16_bf16(b0, qr[d0], p0, 0, 0, 0);
;     p1 = __builtin_amdgcn_mfma_f32_32x32x16_bf16(b1, qr[d0], p1, 0, 0, 0); }
; }
; __device__ __forceinline__ void fix_prompt(f32x16& p0, f32x16& p1, int jt, int lim, int qrow0, int r32, int hi, const float* lut) {
;   if (jt > lim) {
; #pragma unroll
;     for (int r = 0; r < 16; ++r) { p0[r] = -1e30f; p1[r] = -1e30f; }
;   } else if (64 * jt >= qrow0 - 153) {
;     const float* lp = lut + (64 * jt - (qrow0 + r32) + 192);
; #pragma unroll
;     for (int r = 0; r < 16; ++r) { p0[r] += lp[crow(r, hi)]; p1[r] += lp[32 + crow(r, hi)]; }
;   }
.LBB0_447:
	s_setprio 0
	s_and_b32 s14, s10, 1
	s_lshl_b32 s15, s14, 14
	s_add_i32 s23, s15, 0
	v_add3_u32 v81, s23, v70, v69
	ds_read_b128 v[82:85], v81
	ds_read_b128 v[208:211], v81 offset:8192
	v_add3_u32 v81, s23, v71, v69
	ds_read_b128 v[212:215], v81
	ds_read_b128 v[216:219], v81 offset:8192
	v_add3_u32 v81, s23, v72, v69
	ds_read_b128 v[220:223], v81
	ds_read_b128 v[224:227], v81 offset:8192
	v_add3_u32 v81, s23, v73, v69
	ds_read_b128 v[228:231], v81
	ds_read_b128 v[232:235], v81 offset:8192
	v_add3_u32 v81, s23, v74, v69
	ds_read_b128 v[236:239], v81
	ds_read_b128 v[240:243], v81 offset:8192
	v_add3_u32 v81, s23, v75, v69
	ds_read_b128 v[244:247], v81
	ds_read_b128 v[248:251], v81 offset:8192
	s_cmp_gt_u32 s10, s5
	s_waitcnt vmcnt(7) lgkmcnt(11)
	v_mfma_f32_32x32x16_bf16 v[4:19], v[82:85], v[36:39], 0
	s_waitcnt lgkmcnt(10)
	v_mfma_f32_32x32x16_bf16 v[20:35], v[208:211], v[36:39], 0
	v_add3_u32 v81, s23, v76, v69
	ds_read_b128 v[132:135], v81
	ds_read_b128 v[136:139], v81 offset:8192
	s_waitcnt vmcnt(6) lgkmcnt(11)
	v_mfma_f32_32x32x16_bf16 v[4:19], v[212:215], v[40:43], v[4:19]
	s_waitcnt lgkmcnt(10)
	v_mfma_f32_32x32x16_bf16 v[20:35], v[216:219], v[40:43], v[20:35]
	v_add3_u32 v81, s23, v77, v69
	ds_read_b128 v[140:143], v81
	ds_read_b128 v[144:147], v81 offset:8192
	s_waitcnt vmcnt(5) lgkmcnt(11)
	v_mfma_f32_32x32x16_bf16 v[4:19], v[220:223], v[44:47], v[4:19]
	s_waitcnt lgkmcnt(10)
	v_mfma_f32_32x32x16_bf16 v[20:35], v[224:227], v[44:47], v[20:35]
	s_waitcnt vmcnt(4) lgkmcnt(9)
	v_mfma_f32_32x32x16_bf16 v[4:19], v[228:231], v[48:51], v[4:19]
	s_waitcnt lgkmcnt(8)
	v_mfma_f32_32x32x16_bf16 v[20:35], v[232:235], v[48:51], v[20:35]
	s_waitcnt vmcnt(3) lgkmcnt(7)
	v_mfma_f32_32x32x16_bf16 v[4:19], v[236:239], v[52:55], v[4:19]
	s_waitcnt lgkmcnt(6)
	v_mfma_f32_32x32x16_bf16 v[20:35], v[240:243], v[52:55], v[20:35]
	s_waitcnt vmcnt(2) lgkmcnt(5)
	v_mfma_f32_32x32x16_bf16 v[4:19], v[244:247], v[56:59], v[4:19]
	s_waitcnt lgkmcnt(4)
	v_mfma_f32_32x32x16_bf16 v[20:35], v[248:251], v[56:59], v[20:35]
	s_waitcnt vmcnt(1) lgkmcnt(3)
	v_mfma_f32_32x32x16_bf16 v[4:19], v[132:135], v[60:63], v[4:19]
	s_waitcnt lgkmcnt(2)
	v_mfma_f32_32x32x16_bf16 v[20:35], v[136:139], v[60:63], v[20:35]
	s_waitcnt vmcnt(0) lgkmcnt(1)
	v_mfma_f32_32x32x16_bf16 v[4:19], v[140:143], v[64:67], v[4:19]
	s_waitcnt lgkmcnt(0)
	v_mfma_f32_32x32x16_bf16 v[20:35], v[144:147], v[64:67], v[20:35]
	s_cbranch_scc1 .LBB0_450
	s_cmp_lt_i32 s9, s6
	s_cbranch_scc1 .LBB0_451
	v_add_u32_e32 v81, s8, v78
	v_add_u32_e32 v82, 0x20500, v81
	v_add_u32_e32 v84, 0x20580, v81
	ds_read2_b32 v[82:83], v82 offset1:1
	ds_read2_b32 v[84:85], v84 offset1:1
	v_add_u32_e32 v86, 0x20588, v81
	v_add_u32_e32 v88, 0x205a0, v81
	v_add_u32_e32 v90, 0x205a8, v81
	v_add_u32_e32 v92, 0x205c0, v81
	s_waitcnt lgkmcnt(0)
	v_pk_add_f32 v[20:21], v[20:21], v[84:85]
	v_add_u32_e32 v84, 0x20508, v81
	ds_read2_b32 v[84:85], v84 offset1:1
	ds_read2_b32 v[86:87], v86 offset1:1
	v_add_u32_e32 v94, 0x205c8, v81
	v_add_u32_e32 v96, 0x205e0, v81
	v_add_u32_e32 v98, 0x20568, v81
	s_waitcnt lgkmcnt(1)
	v_pk_add_f32 v[6:7], v[6:7], v[84:85]
	s_waitcnt lgkmcnt(0)
	v_pk_add_f32 v[22:23], v[22:23], v[86:87]
	v_add_u32_e32 v86, 0x20520, v81
	ds_read2_b32 v[86:87], v86 offset1:1
	ds_read2_b32 v[88:89], v88 offset1:1
	v_pk_add_f32 v[4:5], v[4:5], v[82:83]
	s_waitcnt lgkmcnt(1)
	v_pk_add_f32 v[8:9], v[8:9], v[86:87]
	s_waitcnt lgkmcnt(0)
	v_pk_add_f32 v[24:25], v[24:25], v[88:89]
	v_add_u32_e32 v88, 0x20528, v81
	ds_read2_b32 v[88:89], v88 offset1:1
	ds_read2_b32 v[90:91], v90 offset1:1
	s_waitcnt lgkmcnt(1)
	v_pk_add_f32 v[10:11], v[10:11], v[88:89]
	s_waitcnt lgkmcnt(0)
	v_pk_add_f32 v[26:27], v[26:27], v[90:91]
	v_add_u32_e32 v90, 0x20540, v81
	ds_read2_b32 v[90:91], v90 offset1:1
	ds_read2_b32 v[92:93], v92 offset1:1
	s_waitcnt lgkmcnt(1)
	v_pk_add_f32 v[12:13], v[12:13], v[90:91]
	s_waitcnt lgkmcnt(0)
	v_pk_add_f32 v[28:29], v[28:29], v[92:93]
	v_add_u32_e32 v92, 0x20548, v81
	ds_read2_b32 v[92:93], v92 offset1:1
	ds_read2_b32 v[94:95], v94 offset1:1
	s_waitcnt lgkmcnt(1)
	v_pk_add_f32 v[14:15], v[14:15], v[92:93]
	s_waitcnt lgkmcnt(0)
	v_pk_add_f32 v[30:31], v[30:31], v[94:95]
	v_add_u32_e32 v94, 0x20560, v81
	ds_read2_b32 v[94:95], v94 offset1:1
	ds_read2_b32 v[96:97], v96 offset1:1
	v_add_u32_e32 v81, 0x205e8, v81
	ds_read2_b32 v[98:99], v98 offset1:1
	s_waitcnt lgkmcnt(2)
	v_pk_add_f32 v[16:17], v[16:17], v[94:95]
	s_waitcnt lgkmcnt(1)
	v_pk_add_f32 v[32:33], v[32:33], v[96:97]
	ds_read2_b32 v[96:97], v81 offset1:1
	s_waitcnt lgkmcnt(1)
	v_pk_add_f32 v[18:19], v[18:19], v[98:99]
	s_waitcnt lgkmcnt(0)
	v_add_f32_e32 v34, v34, v96
	v_add_f32_e32 v35, v35, v97
	s_branch .LBB0_451
